# grid barrier poll sums the eight shard words (readlane + s_add) and compares with 256*n, so no assumption of exactly 32 workgroups per XCC
# baseline (speedup 1.0000x reference)
; #define RUN(k, call) if (lo <= (k) && (k) < hi) { if ((k) > lo) grid.sync(); if (PHMASK & (1 << (k))) { call; } }
; __global__ void __launch_bounds__(NT, 2) fwd_kernel(Params p) {
;     ...
;   RUN(2, phase2(p, lds))
.Lgb2_spin:
	global_load_dword v3, v1, s[6:7] sc1
	s_waitcnt vmcnt(0)
	v_readlane_b32 vcc_lo, v3, 0
	v_readlane_b32 vcc_hi, v3, 1
	s_add_u32 vcc_lo, vcc_lo, vcc_hi
	v_readlane_b32 vcc_hi, v3, 2
	s_add_u32 vcc_lo, vcc_lo, vcc_hi
	v_readlane_b32 vcc_hi, v3, 3
	s_add_u32 vcc_lo, vcc_lo, vcc_hi
	v_readlane_b32 vcc_hi, v3, 4
	s_add_u32 vcc_lo, vcc_lo, vcc_hi
	v_readlane_b32 vcc_hi, v3, 5
	s_add_u32 vcc_lo, vcc_lo, vcc_hi
	v_readlane_b32 vcc_hi, v3, 6
	s_add_u32 vcc_lo, vcc_lo, vcc_hi
	v_readlane_b32 vcc_hi, v3, 7
	s_add_u32 vcc_lo, vcc_lo, vcc_hi
	s_cmp_ge_u32 vcc_lo, 256
	s_cbranch_scc1 .Lgb2_out
	s_sleep 1
	s_branch .Lgb2_spin

; #define RUN(k, call) if (lo <= (k) && (k) < hi) { if ((k) > lo) grid.sync(); if (PHMASK & (1 << (k))) { call; } }
; __global__ void __launch_bounds__(NT, 2) fwd_kernel(Params p) {
;     ...
;   RUN(3, phase3(p, lds))
.Lgb3_spin:
	global_load_dword v3, v1, s[4:5] sc1
	s_waitcnt vmcnt(0)
	v_readlane_b32 vcc_lo, v3, 0
	v_readlane_b32 vcc_hi, v3, 1
	s_add_u32 vcc_lo, vcc_lo, vcc_hi
	v_readlane_b32 vcc_hi, v3, 2
	s_add_u32 vcc_lo, vcc_lo, vcc_hi
	v_readlane_b32 vcc_hi, v3, 3
	s_add_u32 vcc_lo, vcc_lo, vcc_hi
	v_readlane_b32 vcc_hi, v3, 4
	s_add_u32 vcc_lo, vcc_lo, vcc_hi
	v_readlane_b32 vcc_hi, v3, 5
	s_add_u32 vcc_lo, vcc_lo, vcc_hi
	v_readlane_b32 vcc_hi, v3, 6
	s_add_u32 vcc_lo, vcc_lo, vcc_hi
	v_readlane_b32 vcc_hi, v3, 7
	s_add_u32 vcc_lo, vcc_lo, vcc_hi
	s_cmp_ge_u32 vcc_lo, 512
	s_cbranch_scc1 .Lgb3_out
	s_sleep 1
	s_branch .Lgb3_spin

; #define RUN(k, call) if (lo <= (k) && (k) < hi) { if ((k) > lo) grid.sync(); if (PHMASK & (1 << (k))) { call; } }
; __global__ void __launch_bounds__(NT, 2) fwd_kernel(Params p) {
;     ...
;   RUN(4, phase4(p, lds))
.Lgb4_spin:
	global_load_dword v3, v1, s[6:7] sc1
	s_waitcnt vmcnt(0)
	v_readlane_b32 vcc_lo, v3, 0
	v_readlane_b32 vcc_hi, v3, 1
	s_add_u32 vcc_lo, vcc_lo, vcc_hi
	v_readlane_b32 vcc_hi, v3, 2
	s_add_u32 vcc_lo, vcc_lo, vcc_hi
	v_readlane_b32 vcc_hi, v3, 3
	s_add_u32 vcc_lo, vcc_lo, vcc_hi
	v_readlane_b32 vcc_hi, v3, 4
	s_add_u32 vcc_lo, vcc_lo, vcc_hi
	v_readlane_b32 vcc_hi, v3, 5
	s_add_u32 vcc_lo, vcc_lo, vcc_hi
	v_readlane_b32 vcc_hi, v3, 6
	s_add_u32 vcc_lo, vcc_lo, vcc_hi
	v_readlane_b32 vcc_hi, v3, 7
	s_add_u32 vcc_lo, vcc_lo, vcc_hi
	s_cmp_ge_u32 vcc_lo, 768
	s_cbranch_scc1 .Lgb4_out
	s_sleep 1
	s_branch .Lgb4_spin

; #define RUN(k, call) if (lo <= (k) && (k) < hi) { if ((k) > lo) grid.sync(); if (PHMASK & (1 << (k))) { call; } }
; __global__ void __launch_bounds__(NT, 2) fwd_kernel(Params p) {
;     ...
;   RUN(5, phase5(p, lds))
.Lgb5_spin:
	global_load_dword v3, v1, s[4:5] sc1
	s_waitcnt vmcnt(0)
	v_readlane_b32 vcc_lo, v3, 0
	v_readlane_b32 vcc_hi, v3, 1
	s_add_u32 vcc_lo, vcc_lo, vcc_hi
	v_readlane_b32 vcc_hi, v3, 2
	s_add_u32 vcc_lo, vcc_lo, vcc_hi
	v_readlane_b32 vcc_hi, v3, 3
	s_add_u32 vcc_lo, vcc_lo, vcc_hi
	v_readlane_b32 vcc_hi, v3, 4
	s_add_u32 vcc_lo, vcc_lo, vcc_hi
	v_readlane_b32 vcc_hi, v3, 5
	s_add_u32 vcc_lo, vcc_lo, vcc_hi
	v_readlane_b32 vcc_hi, v3, 6
	s_add_u32 vcc_lo, vcc_lo, vcc_hi
	v_readlane_b32 vcc_hi, v3, 7
	s_add_u32 vcc_lo, vcc_lo, vcc_hi
	s_cmp_ge_u32 vcc_lo, 1024
	s_cbranch_scc1 .Lgb5_out
	s_sleep 1
	s_branch .Lgb5_spin

; #define RUN(k, call) if (lo <= (k) && (k) < hi) { if ((k) > lo) grid.sync(); if (PHMASK & (1 << (k))) { call; } }
; __global__ void __launch_bounds__(NT, 2) fwd_kernel(Params p) {
;     ...
;   RUN(6, phase_moe(p, lds, 0))
.Lgb6_spin:
	global_load_dword v3, v1, s[4:5] sc1
	s_waitcnt vmcnt(0)
	v_readlane_b32 vcc_lo, v3, 0
	v_readlane_b32 vcc_hi, v3, 1
	s_add_u32 vcc_lo, vcc_lo, vcc_hi
	v_readlane_b32 vcc_hi, v3, 2
	s_add_u32 vcc_lo, vcc_lo, vcc_hi
	v_readlane_b32 vcc_hi, v3, 3
	s_add_u32 vcc_lo, vcc_lo, vcc_hi
	v_readlane_b32 vcc_hi, v3, 4
	s_add_u32 vcc_lo, vcc_lo, vcc_hi
	v_readlane_b32 vcc_hi, v3, 5
	s_add_u32 vcc_lo, vcc_lo, vcc_hi
	v_readlane_b32 vcc_hi, v3, 6
	s_add_u32 vcc_lo, vcc_lo, vcc_hi
	v_readlane_b32 vcc_hi, v3, 7
	s_add_u32 vcc_lo, vcc_lo, vcc_hi
	s_cmp_ge_u32 vcc_lo, 1280
	s_cbranch_scc1 .Lgb6_out
	s_sleep 1
	s_branch .Lgb6_spin

; #define RUN(k, call) if (lo <= (k) && (k) < hi) { if ((k) > lo) grid.sync(); if (PHMASK & (1 << (k))) { call; } }
; __global__ void __launch_bounds__(NT, 2) fwd_kernel(Params p) {
;     ...
;   RUN(7, phase_moe(p, lds, 1))
.Lgb7_spin:
	global_load_dword v3, v1, s[4:5] sc1
	s_waitcnt vmcnt(0)
	v_readlane_b32 vcc_lo, v3, 0
	v_readlane_b32 vcc_hi, v3, 1
	s_add_u32 vcc_lo, vcc_lo, vcc_hi
	v_readlane_b32 vcc_hi, v3, 2
	s_add_u32 vcc_lo, vcc_lo, vcc_hi
	v_readlane_b32 vcc_hi, v3, 3
	s_add_u32 vcc_lo, vcc_lo, vcc_hi
	v_readlane_b32 vcc_hi, v3, 4
	s_add_u32 vcc_lo, vcc_lo, vcc_hi
	v_readlane_b32 vcc_hi, v3, 5
	s_add_u32 vcc_lo, vcc_lo, vcc_hi
	v_readlane_b32 vcc_hi, v3, 6
	s_add_u32 vcc_lo, vcc_lo, vcc_hi
	v_readlane_b32 vcc_hi, v3, 7
	s_add_u32 vcc_lo, vcc_lo, vcc_hi
	s_cmp_ge_u32 vcc_lo, 1536
	s_cbranch_scc1 .Lgb7_out
	s_sleep 1
	s_branch .Lgb7_spin

; #define RUN(k, call) if (lo <= (k) && (k) < hi) { if ((k) > lo) grid.sync(); if (PHMASK & (1 << (k))) { call; } }
; __global__ void __launch_bounds__(NT, 2) fwd_kernel(Params p) {
;     ...
;   RUN(8, phase_moe(p, lds, 2))
.Lgb8_spin:
	global_load_dword v3, v1, s[4:5] sc1
	s_waitcnt vmcnt(0)
	v_readlane_b32 vcc_lo, v3, 0
	v_readlane_b32 vcc_hi, v3, 1
	s_add_u32 vcc_lo, vcc_lo, vcc_hi
	v_readlane_b32 vcc_hi, v3, 2
	s_add_u32 vcc_lo, vcc_lo, vcc_hi
	v_readlane_b32 vcc_hi, v3, 3
	s_add_u32 vcc_lo, vcc_lo, vcc_hi
	v_readlane_b32 vcc_hi, v3, 4
	s_add_u32 vcc_lo, vcc_lo, vcc_hi
	v_readlane_b32 vcc_hi, v3, 5
	s_add_u32 vcc_lo, vcc_lo, vcc_hi
	v_readlane_b32 vcc_hi, v3, 6
	s_add_u32 vcc_lo, vcc_lo, vcc_hi
	v_readlane_b32 vcc_hi, v3, 7
	s_add_u32 vcc_lo, vcc_lo, vcc_hi
	s_cmp_ge_u32 vcc_lo, 1792
	s_cbranch_scc1 .Lgb8_out
	s_sleep 1
	s_branch .Lgb8_spin
